# grid.sync (cg single-counter spin) replaced by inlined XCD-hierarchical barrier; RWKV next-block load wait ladder deferred past the MFMA loop
# speedup vs baseline: 1.2624x; 1.0108x over previous
.LBB0_586:
.Lrw_entry:
	v_readfirstlane_b32 s0, v180
	s_nop 1
	s_cmpk_ge_u32 s0, 0x100
	s_cbranch_scc1 .Lrw_done
	v_and_b32_e32 v222, 15, v180
	v_bfe_u32 v223, v180, 4, 2
	v_lshrrev_b32_e32 v240, 6, v180
	v_and_b32_e32 v176, 7, v222
	v_mul_u32_u24_e32 v176, 0x110, v176
	v_and_b32_e32 v177, 8, v222
	v_mul_u32_u24_e32 v177, 0x880, v177
	v_lshl_add_u32 v168, v223, 4, v176
	v_add_u32_e32 v168, v168, v177
	v_lshlrev_b32_e32 v178, 6, v240
	v_lshl_add_u32 v178, v222, 2, v178
	v_lshl_add_u32 v169, v223, 8, v178
	v_add_u32_e32 v169, s41, v169
	v_lshl_add_u32 v175, v223, 10, v178
	v_add_u32_e32 v175, 0x1f000, v175
	v_mov_b32_e32 v170, 0x15800
	v_lshlrev_b32_e32 v176, 5, v222
	v_lshl_add_u32 v176, v223, 2, v176
	v_and_b32_e32 v177, 8, v222
	v_lshl_add_u32 v172, v177, 5, v176
	v_add_u32_e32 v171, 0x15900, v172
	v_add_u32_e32 v172, 0x15800, v172
	v_mul_u32_u24_e32 v176, 0x110, v223
	v_lshl_add_u32 v173, v222, 2, v176
	v_add_u32_e32 v173, 0x8800, v173
	v_add_u32_e32 v2, 0x440, v173
	v_add_u32_e32 v3, 0x4400, v173
	v_add_u32_e32 v5, 0x4840, v173
	v_lshlrev_b32_e32 v174, 4, v223
	v_add_u32_e32 v174, 0x11000, v174
	v_cmp_eq_u32_e32 vcc, 1, v223
	v_cmp_eq_u32_e64 s[4:5], 2, v223
	v_cmp_eq_u32_e64 s[6:7], 3, v223
	s_mov_b32 s8, 0
	s_mov_b32 s9, -1
	v_mov_b32_e32 v198, 1.0
	v_mov_b32_e32 v199, 1.0
	v_mov_b32_e32 v200, 1.0
	v_mov_b32_e32 v201, 1.0
	v_mov_b32_e32 v202, 1.0
	v_mov_b32_e32 v203, 1.0
	v_mov_b32_e32 v204, 1.0
	v_mov_b32_e32 v205, 1.0
	v_mov_b32_e32 v206, 1.0
	v_mov_b32_e32 v207, 1.0
	v_mov_b32_e32 v208, 1.0
	v_mov_b32_e32 v209, 1.0
	v_mov_b32_e32 v210, 1.0
	v_mov_b32_e32 v211, 1.0
	v_mov_b32_e32 v212, 1.0
	v_mov_b32_e32 v213, 1.0
	ds_read_b128 v[44:47], v168 offset:0
	ds_read_b128 v[48:51], v168 offset:64
	ds_read_b128 v[68:71], v168 offset:128
	ds_read_b128 v[96:99], v168 offset:192
	ds_read_b32 v216, v171 offset:0
	ds_read_b32 v217, v171 offset:16
	ds_read_b32 v214, v169 offset:0
	ds_read_b32 v215, v169 offset:1024
	ds_read_b128 v[124:127], v170 offset:32
	ds_read_b128 v[128:131], v170 offset:64
	ds_read_b128 v[132:135], v170 offset:96
	ds_read_b128 v[136:139], v170 offset:128
	ds_read_b128 v[144:147], v170 offset:160
	ds_read_b128 v[148:151], v170 offset:176
	ds_read_b128 v[152:155], v170 offset:192
	ds_read_b128 v[156:159], v170 offset:208
	ds_read_b128 v[160:163], v170 offset:224
	ds_read_b128 v[164:167], v170 offset:240
	ds_read_b32 v218, v172 offset:0
	ds_read_b32 v219, v172 offset:16
	ds_read2_b32 v[182:183], v173 offset0:0 offset1:16
	ds_read2_b32 v[184:185], v173 offset0:32 offset1:48
	ds_read2_b32 v[186:187], v2 offset0:0 offset1:16
	ds_read2_b32 v[188:189], v2 offset0:32 offset1:48
	ds_read2_b32 v[190:191], v3 offset0:0 offset1:16
	ds_read2_b32 v[192:193], v3 offset0:32 offset1:48
	ds_read2_b32 v[194:195], v5 offset0:0 offset1:16
	ds_read2_b32 v[196:197], v5 offset0:32 offset1:48
	s_mov_b32 s1, 0
	s_waitcnt lgkmcnt(0)
.Lrw_loop:
	s_waitcnt lgkmcnt(4)
	v_pk_mul_f32 v[224:225], v[224:225], v[198:199]
	v_pk_mul_f32 v[226:227], v[226:227], v[200:201]
	v_pk_mul_f32 v[228:229], v[228:229], v[202:203]
	v_pk_mul_f32 v[230:231], v[230:231], v[204:205]
	v_mfma_f32_16x16x4_f32 v[36:39], v44, v224, 0
	v_mfma_f32_16x16x4_f32 v[40:43], v45, v225, 0
	v_mfma_f32_16x16x4_f32 v[36:39], v46, v226, v[36:39]
	v_mfma_f32_16x16x4_f32 v[40:43], v47, v227, v[40:43]
	v_pk_mul_f32 v[232:233], v[232:233], v[206:207]
	v_pk_mul_f32 v[234:235], v[234:235], v[208:209]
	v_mfma_f32_16x16x4_f32 v[36:39], v48, v228, v[36:39]
	v_mfma_f32_16x16x4_f32 v[40:43], v49, v229, v[40:43]
	v_mfma_f32_16x16x4_f32 v[36:39], v50, v230, v[36:39]
	v_mfma_f32_16x16x4_f32 v[40:43], v51, v231, v[40:43]
	v_pk_mul_f32 v[236:237], v[236:237], v[210:211]
	v_pk_mul_f32 v[238:239], v[238:239], v[212:213]
	v_mfma_f32_16x16x4_f32 v[36:39], v68, v232, v[36:39]
	v_mfma_f32_16x16x4_f32 v[40:43], v69, v233, v[40:43]
	v_mfma_f32_16x16x4_f32 v[36:39], v70, v234, v[36:39]
	v_mfma_f32_16x16x4_f32 v[40:43], v71, v235, v[40:43]
	v_mfma_f32_16x16x4_f32 v[36:39], v96, v236, v[36:39]
	v_mfma_f32_16x16x4_f32 v[40:43], v97, v237, v[40:43]
	v_mfma_f32_16x16x4_f32 v[36:39], v98, v238, v[36:39]
	v_mfma_f32_16x16x4_f32 v[40:43], v99, v239, v[40:43]
	v_mfma_f32_16x16x4_f32 v[36:39], v216, v214, v[36:39]
	v_mfma_f32_16x16x4_f32 v[40:43], v217, v215, v[40:43]
	ds_read_b128 v[44:47], v168 offset:2176
	ds_read_b128 v[48:51], v168 offset:2240
	ds_read_b128 v[68:71], v168 offset:2304
	ds_read_b128 v[96:99], v168 offset:2368
	ds_read_b32 v216, v171 offset:1024
	ds_read_b32 v217, v171 offset:1040
	ds_read_b128 v[198:201], v174 offset:0
	ds_read_b128 v[202:205], v174 offset:64
	ds_read_b128 v[206:209], v174 offset:128
	ds_read_b128 v[210:213], v174 offset:192
	v_mfma_f32_16x16x4_f32 v[224:227], v190, v214, v[224:227]
	v_mfma_f32_16x16x4_f32 v[224:227], v194, v215, v[224:227]
	v_mfma_f32_16x16x4_f32 v[228:231], v191, v214, v[228:231]
	v_mfma_f32_16x16x4_f32 v[228:231], v195, v215, v[228:231]
	v_mfma_f32_16x16x4_f32 v[232:235], v192, v214, v[232:235]
	v_mfma_f32_16x16x4_f32 v[232:235], v196, v215, v[232:235]
	v_mfma_f32_16x16x4_f32 v[236:239], v193, v214, v[236:239]
	v_mfma_f32_16x16x4_f32 v[236:239], v197, v215, v[236:239]
	ds_read_b32 v214, v169 offset:2048
	ds_read_b32 v215, v169 offset:3072
	v_pk_add_f32 v[80:81], v[36:37], v[40:41]
	v_pk_add_f32 v[82:83], v[38:39], v[42:43]
	v_pk_add_f32 v[84:85], v[36:37], v[40:41]
	v_pk_add_f32 v[86:87], v[38:39], v[42:43]
	v_pk_add_f32 v[36:37], v[36:37], v[40:41]
	v_pk_add_f32 v[38:39], v[38:39], v[42:43]
	v_permlane32_swap_b32_e32 v80, v84
	v_permlane32_swap_b32_e32 v81, v85
	v_permlane32_swap_b32_e32 v82, v86
	v_permlane32_swap_b32_e32 v83, v87
	v_mov_b32_e32 v88, v80
	v_mov_b32_e32 v89, v81
	v_mov_b32_e32 v90, v82
	v_mov_b32_e32 v91, v83
	s_nop 0
	v_permlane16_swap_b32_e32 v80, v88
	v_permlane16_swap_b32_e32 v81, v89
	v_permlane16_swap_b32_e32 v82, v90
	v_permlane16_swap_b32_e32 v83, v91
	v_fmac_f32_e32 v81, v124, v80
	v_fmac_f32_e32 v82, v128, v80
	v_fmac_f32_e32 v83, v132, v80
	v_fmac_f32_e32 v88, v136, v80
	v_fmac_f32_e32 v89, v144, v80
	v_fmac_f32_e32 v90, v152, v80
	v_fmac_f32_e32 v91, v160, v80
	v_fmac_f32_e32 v82, v129, v81
	v_fmac_f32_e32 v83, v133, v81
	v_fmac_f32_e32 v88, v137, v81
	v_fmac_f32_e32 v89, v145, v81
	v_fmac_f32_e32 v90, v153, v81
	v_fmac_f32_e32 v91, v161, v81
	v_fmac_f32_e32 v83, v134, v82
	v_fmac_f32_e32 v88, v138, v82
	v_fmac_f32_e32 v89, v146, v82
	v_fmac_f32_e32 v90, v154, v82
	v_fmac_f32_e32 v91, v162, v82
	v_fmac_f32_e32 v88, v139, v83
	v_fmac_f32_e32 v89, v147, v83
	v_fmac_f32_e32 v90, v155, v83
	v_fmac_f32_e32 v91, v163, v83
	v_fmac_f32_e32 v89, v148, v88
	v_fmac_f32_e32 v90, v156, v88
	v_fmac_f32_e32 v91, v164, v88
	v_fmac_f32_e32 v90, v157, v89
	v_fmac_f32_e32 v91, v165, v89
	v_fmac_f32_e32 v91, v166, v90
	ds_read_b128 v[124:127], v170 offset:1056
	ds_read_b128 v[128:131], v170 offset:1088
	ds_read_b128 v[132:135], v170 offset:1120
	ds_read_b128 v[136:139], v170 offset:1152
	ds_read_b128 v[144:147], v170 offset:1184
	ds_read_b128 v[148:151], v170 offset:1200
	ds_read_b128 v[152:155], v170 offset:1216
	ds_read_b128 v[156:159], v170 offset:1232
	ds_read_b128 v[160:163], v170 offset:1248
	ds_read_b128 v[164:167], v170 offset:1264
	v_cndmask_b32_e32 v220, v80, v81, vcc
	v_cndmask_b32_e64 v220, v220, v82, s[4:5]
	v_cndmask_b32_e64 v220, v220, v83, s[6:7]
	v_cndmask_b32_e32 v221, v88, v89, vcc
	v_cndmask_b32_e64 v221, v221, v90, s[4:5]
	v_cndmask_b32_e64 v221, v221, v91, s[6:7]
	s_nop 1
	v_mfma_f32_16x16x4_f32 v[84:87], v218, v220, v[36:39]
	v_mfma_f32_16x16x4_f32 v[84:87], v219, v221, v[84:87]
	ds_read_b32 v218, v172 offset:1024
	ds_read_b32 v219, v172 offset:1040
	v_mfma_f32_16x16x4_f32 v[224:227], v182, v220, v[224:227]
	v_mfma_f32_16x16x4_f32 v[224:227], v186, v221, v[224:227]
	v_mfma_f32_16x16x4_f32 v[228:231], v183, v220, v[228:231]
	v_mfma_f32_16x16x4_f32 v[228:231], v187, v221, v[228:231]
	v_mfma_f32_16x16x4_f32 v[232:235], v184, v220, v[232:235]
	v_mfma_f32_16x16x4_f32 v[232:235], v188, v221, v[232:235]
	v_mfma_f32_16x16x4_f32 v[236:239], v185, v220, v[236:239]
	v_mfma_f32_16x16x4_f32 v[236:239], v189, v221, v[236:239]
	v_add_u32_e32 v173, 0x880, v173
	v_add_u32_e32 v2, 0x880, v2
	v_add_u32_e32 v3, 0x880, v3
	v_add_u32_e32 v5, 0x880, v5
	ds_read2_b32 v[182:183], v173 offset0:0 offset1:16
	ds_read2_b32 v[184:185], v173 offset0:32 offset1:48
	ds_read2_b32 v[186:187], v2 offset0:0 offset1:16
	ds_read2_b32 v[188:189], v2 offset0:32 offset1:48
	ds_read2_b32 v[190:191], v3 offset0:0 offset1:16
	ds_read2_b32 v[192:193], v3 offset0:32 offset1:48
	ds_read2_b32 v[194:195], v5 offset0:0 offset1:16
	ds_read2_b32 v[196:197], v5 offset0:32 offset1:48
	s_mov_b64 exec, s[8:9]
	ds_write_b32 v175, v84 offset:0
	ds_write_b32 v175, v85 offset:256
	ds_write_b32 v175, v86 offset:512
	ds_write_b32 v175, v87 offset:768
	s_mov_b64 exec, -1
	v_add_u32_e32 v168, 0x880, v168
	v_add_u32_e32 v169, 0x800, v169
	v_add_u32_e32 v170, 0x400, v170
	v_add_u32_e32 v171, 0x400, v171
	v_add_u32_e32 v172, 0x400, v172
	v_add_u32_e32 v174, 0x100, v174
	v_add_u32_e32 v175, 0x800, v175
	s_add_i32 s1, s1, 1
	s_cmp_lg_u32 s1, 8
	s_cbranch_scc1 .Lrw_loop
	s_waitcnt lgkmcnt(0)
	s_nop 7
	v_pk_mul_f32 v[224:225], v[224:225], v[198:199]
	v_pk_mul_f32 v[226:227], v[226:227], v[200:201]
	v_pk_mul_f32 v[228:229], v[228:229], v[202:203]
	v_pk_mul_f32 v[230:231], v[230:231], v[204:205]
	v_pk_mul_f32 v[232:233], v[232:233], v[206:207]
	v_pk_mul_f32 v[234:235], v[234:235], v[208:209]
	v_pk_mul_f32 v[236:237], v[236:237], v[210:211]
	v_pk_mul_f32 v[238:239], v[238:239], v[212:213]
.Lrw_done:
	s_cmp_lg_u32 s40, 31
	s_cbranch_scc0 .Lrw_noladder
	s_waitcnt vmcnt(39)
	v_lshlrev_b32_e32 v44, 16, v18
	s_waitcnt vmcnt(38)
	v_lshlrev_b32_e32 v1, 16, v1
	s_waitcnt vmcnt(37)
	v_lshlrev_b32_e32 v46, 16, v19
	s_waitcnt vmcnt(36)
	v_lshlrev_b32_e32 v48, 16, v20
	s_waitcnt vmcnt(34)
	v_lshlrev_b32_e32 v45, 16, v21
	s_waitcnt vmcnt(33)
	v_lshlrev_b32_e32 v47, 16, v22
	s_waitcnt vmcnt(32)
	v_lshlrev_b32_e32 v51, 16, v23
	s_waitcnt vmcnt(30)
	v_lshlrev_b32_e32 v54, 16, v24
	s_waitcnt vmcnt(29)
	v_lshlrev_b32_e32 v52, 16, v25
	s_waitcnt vmcnt(28)
	v_lshlrev_b32_e32 v50, 16, v27
	s_waitcnt vmcnt(26)
	v_lshlrev_b32_e32 v49, 16, v28
	s_waitcnt vmcnt(25)
	v_lshlrev_b32_e32 v53, 16, v29
	s_waitcnt vmcnt(23)
	v_lshlrev_b32_e32 v57, 16, v31
	s_waitcnt vmcnt(22)
	v_lshlrev_b32_e32 v60, 16, v32
	s_waitcnt vmcnt(21)
	v_lshlrev_b32_e32 v58, 16, v33
	s_waitcnt vmcnt(20)
	v_lshlrev_b32_e32 v56, 16, v55
	v_lshlrev_b32_e32 v55, 16, v30
	s_waitcnt vmcnt(17)
	v_lshlrev_b32_e32 v59, 16, v59
	s_waitcnt vmcnt(16)
	v_lshlrev_b32_e32 v61, 16, v61
	s_waitcnt vmcnt(15)
	v_lshlrev_b32_e32 v62, 16, v62
	s_waitcnt vmcnt(14)
	v_lshlrev_b32_e32 v63, 16, v63
	s_waitcnt vmcnt(13)
	v_lshlrev_b32_e32 v66, 16, v66
	s_waitcnt vmcnt(12)
	v_lshlrev_b32_e32 v64, 16, v64
	s_waitcnt vmcnt(11)
	v_lshlrev_b32_e32 v65, 16, v6
	s_waitcnt vmcnt(9)
	v_lshlrev_b32_e32 v67, 16, v7
	s_waitcnt vmcnt(8)
	v_lshlrev_b32_e32 v70, 16, v12
	s_waitcnt vmcnt(7)
	v_lshlrev_b32_e32 v72, 16, v13
	s_waitcnt vmcnt(6)
	v_lshlrev_b32_e32 v68, 16, v16
	s_waitcnt vmcnt(5)
	v_lshlrev_b32_e32 v69, 16, v17
	s_waitcnt vmcnt(4)
	v_lshlrev_b32_e32 v71, 16, v8
	s_waitcnt vmcnt(2)
	v_lshlrev_b32_e32 v74, 16, v9
	s_waitcnt vmcnt(1)
	v_lshlrev_b32_e32 v73, 16, v4

.LBB0_590:
	s_waitcnt vmcnt(0)
	s_barrier
	s_mov_b64 s[0:1], exec
	v_readlane_b32 s4, v242, 6
	v_readlane_b32 s5, v242, 7
	s_and_b64 s[4:5], s[0:1], s[4:5]
	s_mov_b64 exec, s[4:5]
	s_cbranch_execz .Lgs_659
	s_add_i32 s3, 0, 0x27ff0
	v_mov_b32_e32 v0, s3
	s_waitcnt vmcnt(0) expcnt(0) lgkmcnt(0)
	ds_read_b32 v2, v0
	s_add_i32 s3, 0, 0x27ff4
	v_mov_b32_e32 v0, s3
	ds_read_b32 v0, v0
	s_waitcnt lgkmcnt(1)
	v_cmp_ne_u32_e32 vcc, 0, v2
	s_cbranch_vccnz .Lgs_623
	s_add_u32 s4, s34, 0x1f220200
	s_addc_u32 s5, s35, 0
	s_add_u32 s6, s34, 0x1f220400
	s_addc_u32 s7, s35, 0
	s_add_u32 s8, s34, 0x1f220500
	s_addc_u32 s9, s35, 0
	s_add_u32 s10, s34, 0x1f220600
	s_addc_u32 s11, s35, 0
	s_add_u32 s12, s34, 0x1f220700
	s_addc_u32 s13, s35, 0
	s_add_u32 s14, s34, 0x1f220800
	s_addc_u32 s15, s35, 0
	s_add_u32 s60, s34, 0x1f220900
	s_addc_u32 s61, s35, 0
	s_add_u32 s26, s34, 0x1f220a00
	s_addc_u32 s27, s35, 0
	s_add_u32 s42, s34, 0x1f220b00
	s_addc_u32 s43, s35, 0
	s_add_u32 s44, s34, 0x1f220c00
	s_addc_u32 s45, s35, 0
	s_add_u32 s46, s34, 0x1f220d00
	s_addc_u32 s47, s35, 0
	s_add_u32 s48, s34, 0x1f220e00
	s_addc_u32 s49, s35, 0
	s_add_u32 s50, s34, 0x1f220f00
	s_addc_u32 s51, s35, 0
	s_add_u32 s52, s34, 0x1f221000
	s_addc_u32 s53, s35, 0
	s_add_u32 s54, s34, 0x1f221100
	s_addc_u32 s55, s35, 0
	s_add_u32 s56, s34, 0x1f221200
	v_readlane_b32 s3, v242, 0
	s_addc_u32 s57, s35, 0
	s_mul_i32 s3, s19, s3
	s_add_u32 s58, s34, 0x1f221300
	s_mul_i32 s3, s3, s18
	s_addc_u32 s59, s35, 0
	s_mov_b32 s16, 1
	v_mov_b32_e32 v16, 0
	s_branch .Lgs_611

.Lgs_611:
	global_load_dword v15, v16, s[6:7] sc1
	s_waitcnt lgkmcnt(0)
	global_load_dword v0, v16, s[8:9] sc1
	global_load_dword v1, v16, s[10:11] sc1
	global_load_dword v2, v16, s[12:13] sc1
	global_load_dword v3, v16, s[14:15] sc1
	global_load_dword v4, v16, s[60:61] sc1
	global_load_dword v5, v16, s[26:27] sc1
	global_load_dword v6, v16, s[42:43] sc1
	global_load_dword v7, v16, s[44:45] sc1
	global_load_dword v8, v16, s[46:47] sc1
	global_load_dword v9, v16, s[48:49] sc1
	global_load_dword v10, v16, s[50:51] sc1
	global_load_dword v11, v16, s[52:53] sc1
	global_load_dword v12, v16, s[54:55] sc1
	global_load_dword v13, v16, s[56:57] sc1
	global_load_dword v14, v16, s[58:59] sc1
	s_mov_b64 s[60:61], -1
	s_mov_b64 s[62:63], -1
	s_waitcnt vmcnt(14)
	v_add_u32_e32 v17, v0, v15
	s_waitcnt vmcnt(13)
	v_add_u32_e32 v17, v17, v1
	s_waitcnt vmcnt(12)
	v_add_u32_e32 v17, v17, v2
	s_waitcnt vmcnt(11)
	v_add_u32_e32 v17, v17, v3
	s_waitcnt vmcnt(10)
	v_add_u32_e32 v17, v17, v4
	s_waitcnt vmcnt(9)
	v_add_u32_e32 v17, v17, v5
	s_waitcnt vmcnt(8)
	v_add_u32_e32 v17, v17, v6
	s_waitcnt vmcnt(7)
	v_add_u32_e32 v17, v17, v7
	s_waitcnt vmcnt(6)
	v_add_u32_e32 v17, v17, v8
	s_waitcnt vmcnt(5)
	v_add_u32_e32 v17, v17, v9
	s_waitcnt vmcnt(4)
	v_add_u32_e32 v17, v17, v10
	s_waitcnt vmcnt(3)
	v_add_u32_e32 v17, v17, v11
	s_waitcnt vmcnt(2)
	v_add_u32_e32 v17, v17, v12
	s_waitcnt vmcnt(1)
	v_add_u32_e32 v17, v17, v13
	s_waitcnt vmcnt(0)
	v_add_u32_e32 v17, v17, v14
	v_cmp_eq_u32_e32 vcc, s3, v17
	s_cbranch_vccnz .Lgs_610
	s_and_b32 s17, s16, 0xff
	s_cmp_eq_u32 s17, 0
	s_mov_b64 s[64:65], -1
	s_sleep 1
	s_cbranch_scc1 .Lgs_615
	s_and_b64 vcc, exec, s[64:65]
	s_cbranch_vccz .Lgs_610

.Lgs_628:
	s_and_b64 s[16:17], exec, s[26:27]
	s_or_b64 s[14:15], s[16:17], s[14:15]
	s_andn2_b64 s[16:17], s[60:61], exec
	s_and_b64 s[60:61], s[42:43], exec
	s_or_b64 s[60:61], s[16:17], s[60:61]
	s_andn2_b64 exec, exec, s[14:15]
	s_cbranch_execz .Lgs_635

.Lgs_635:
	s_or_b64 exec, exec, s[14:15]
	s_xor_b64 s[12:13], s[60:61], -1
	s_and_saveexec_b64 s[14:15], s[12:13]
	s_xor_b64 s[14:15], exec, s[14:15]
	s_cbranch_execz .Lgs_638
	s_mov_b64 s[12:13], exec
	v_mbcnt_lo_u32_b32 v0, s12, 0
	v_mbcnt_hi_u32_b32 v0, s13, v0
	v_cmp_eq_u32_e32 vcc, 0, v0
	s_and_b64 s[14:15], exec, vcc
	s_mov_b64 exec, s[14:15]
	s_cbranch_execz .Lgs_638
	s_bcnt1_i32_b64 s3, s[12:13]
	v_mov_b32_e32 v0, 0
	v_mov_b32_e32 v1, s3
	global_atomic_add v0, v1, s[10:11]

.Lgs_645:
	s_xor_b64 s[16:17], s[26:27], -1
	s_and_b64 s[26:27], exec, s[44:45]
	s_or_b64 s[14:15], s[26:27], s[14:15]
	s_andn2_b64 s[60:61], s[60:61], exec
	s_and_b64 s[16:17], s[16:17], exec
	s_or_b64 s[60:61], s[60:61], s[16:17]
	s_andn2_b64 exec, exec, s[14:15]
	s_cbranch_execz .Lgs_652

.Lgs_652:
	s_or_b64 exec, exec, s[14:15]
	s_and_b64 s[14:15], s[60:61], exec

.Lgs_659:
.LBB0_600:
	s_or_b64 exec, exec, s[0:1]
	s_waitcnt lgkmcnt(0)
	s_mul_i32 s14, s18, 24
	v_mov_b32_e32 v9, v180
	s_barrier
	s_mov_b32 s3, 0x8000
	v_ashrrev_i32_e32 v0, 6, v9
	v_add_u32_e32 v8, s95, v0
	v_cmp_gt_i32_e32 vcc, s3, v8
	s_and_saveexec_b64 s[0:1], vcc
	s_cbranch_execz .LBB0_607
	v_lshlrev_b32_e32 v0, 5, v9
	s_waitcnt vmcnt(4)
	v_and_b32_e32 v10, 0x1e0, v0
	global_load_dwordx4 v[0:3], v10, s[20:21]
	global_load_dwordx4 v[4:7], v10, s[20:21] offset:16
	v_lshlrev_b32_e32 v9, 3, v9
	v_and_b32_e32 v9, 0x1f8, v9
	v_lshlrev_b32_e32 v10, 2, v9
	v_mov_b32_e32 v11, 0
	v_lshl_add_u64 v[12:13], s[34:35], 0, v[10:11]
	s_mov_b64 s[4:5], 0x10220000
	v_lshlrev_b32_e32 v10, 1, v9
	v_lshl_add_u64 v[44:45], v[12:13], 0, s[4:5]
	v_lshl_add_u64 v[10:11], s[34:35], 0, v[10:11]
	s_mov_b64 s[4:5], 0x14220000
	v_lshl_add_u64 v[46:47], v[10:11], 0, s[4:5]
	s_mov_b64 s[4:5], 0x17220000
	s_add_i32 s11, s33, s33
	v_lshl_add_u64 v[48:49], v[10:11], 0, s[4:5]
	s_lshl_b32 s8, s18, 4
	s_mov_b64 s[4:5], 0
	s_movk_i32 s9, 0x7fff
	v_mov_b32_e32 v56, 0x358637bd
	s_mov_b32 s10, 0x800000
	s_add_i32 s11, s11, s33
	s_branch .LBB0_603
